# v20 plus non-temporal stores for the input-projection epilogue (406 MB/layer streamed output)
# speedup vs baseline: 1.0291x; 1.0021x over previous
; DI void gemm256_tile(const Params& p, int mode, int layer, const u16* R, const u16* Cc, int brow, int bcol, lchar* shm, int tid_in, int wid) {
;     ...
;   if (mode == EPI_PROJ) {
; #pragma unroll
;     for (int ai = 0; ai < 2; ++ai)
; #pragma unroll
;       for (int bj = 0; bj < 2; ++bj)
; #pragma unroll
;         for (int n = 0; n < 2; ++n) {
;           const int nc = brow + ai * 128 + wr * 64 + fq * 16, tok = bcol + bj * 128 + wc * 32 + n * 16 + fr;
;           u16* dst = W_PROJ(p) + (size_t)tok * INC + nc;
; #pragma unroll
;           for (int q = 0; q < 2; ++q) {
;             const f32x4 va = acc[ai][bj][2 * q][n], vb2 = acc[ai][bj][2 * q + 1][n];
;             *(u32x4*)(dst + 8 * q) = (u32x4){pack2(va[0], va[1]), pack2(va[2], va[3]), pack2(vb2[0], vb2[1]), pack2(vb2[2], vb2[3])};
;           }
;         }
;   } else if (mode == EPI_VT) {
; #pragma unroll
;     for (int ai = 0; ai < 2; ++ai)
; #pragma unroll
;       for (int bj = 0; bj < 2; ++bj)
; #pragma unroll
;         for (int n = 0; n < 2; ++n) {
;           const int tok = brow + ai * 128 + wr * 64 + fq * 16, nn = bcol + bj * 128 + wc * 32 + n * 16 + fr - 1024;
;           const int b = tok / LSEQ, pos = tok - b * LSEQ;
;           u16* dst = W_VT(p) + ((size_t)(b * 512 + nn)) * LP + pos;
; #pragma unroll
;           for (int q = 0; q < 2; ++q) {
;             const f32x4 va = acc[ai][bj][2 * q][n], vb2 = acc[ai][bj][2 * q + 1][n];
;             *(u32x4*)(dst + 8 * q) = (u32x4){pack2(va[0], va[1]), pack2(va[2], va[3]), pack2(vb2[0], vb2[1]), pack2(vb2[2], vb2[3])};
;           }
;         }
.LBB0_241:
	s_andn2_b64 vcc, exec, s[36:37]
	s_cbranch_vccnz .LBB0_205
	s_mov_b64 s[0:1], -1
	s_cmp_lg_u32 s11, 1
	v_cvt_pk_bf16_f32 v144, v12, v13
	v_cvt_pk_bf16_f32 v145, v14, v15
	v_cvt_pk_bf16_f32 v146, v20, v21
	v_cvt_pk_bf16_f32 v147, v22, v23
	v_cvt_pk_bf16_f32 v140, v24, v25
	v_cvt_pk_bf16_f32 v141, v26, v27
	v_cvt_pk_bf16_f32 v142, v32, v33
	v_cvt_pk_bf16_f32 v143, v34, v35
	v_cvt_pk_bf16_f32 v136, v0, v1
	v_cvt_pk_bf16_f32 v137, v2, v3
	v_cvt_pk_bf16_f32 v138, v4, v5
	v_cvt_pk_bf16_f32 v139, v6, v7
	v_cvt_pk_bf16_f32 v132, v8, v9
	v_cvt_pk_bf16_f32 v133, v10, v11
	v_cvt_pk_bf16_f32 v134, v16, v17
	v_cvt_pk_bf16_f32 v135, v18, v19
	v_cvt_pk_bf16_f32 v128, v44, v45
	v_cvt_pk_bf16_f32 v129, v46, v47
	v_cvt_pk_bf16_f32 v130, v52, v53
	v_cvt_pk_bf16_f32 v131, v54, v55
	v_cvt_pk_bf16_f32 v52, v56, v57
	v_cvt_pk_bf16_f32 v53, v58, v59
	v_cvt_pk_bf16_f32 v54, v60, v61
	v_cvt_pk_bf16_f32 v55, v62, v63
	v_cvt_pk_bf16_f32 v44, v28, v29
	v_cvt_pk_bf16_f32 v45, v30, v31
	v_cvt_pk_bf16_f32 v46, v36, v37
	v_cvt_pk_bf16_f32 v47, v38, v39
	v_cvt_pk_bf16_f32 v32, v40, v41
	v_cvt_pk_bf16_f32 v33, v42, v43
	v_cvt_pk_bf16_f32 v34, v48, v49
	v_cvt_pk_bf16_f32 v35, v50, v51
	v_cvt_pk_bf16_f32 v28, v84, v85
	v_cvt_pk_bf16_f32 v29, v86, v87
	v_cvt_pk_bf16_f32 v30, v96, v97
	v_cvt_pk_bf16_f32 v31, v98, v99
	v_cvt_pk_bf16_f32 v24, v108, v109
	v_cvt_pk_bf16_f32 v25, v110, v111
	v_cvt_pk_bf16_f32 v26, v116, v117
	v_cvt_pk_bf16_f32 v27, v118, v119
	v_cvt_pk_bf16_f32 v20, v64, v65
	v_cvt_pk_bf16_f32 v21, v66, v67
	v_cvt_pk_bf16_f32 v22, v68, v69
	v_cvt_pk_bf16_f32 v23, v70, v71
	v_cvt_pk_bf16_f32 v16, v76, v77
	v_cvt_pk_bf16_f32 v17, v78, v79
	v_cvt_pk_bf16_f32 v18, v88, v89
	v_cvt_pk_bf16_f32 v19, v90, v91
	v_cvt_pk_bf16_f32 v12, v100, v101
	v_cvt_pk_bf16_f32 v13, v102, v103
	v_cvt_pk_bf16_f32 v14, v112, v113
	v_cvt_pk_bf16_f32 v15, v114, v115
	v_cvt_pk_bf16_f32 v8, v120, v121
	v_cvt_pk_bf16_f32 v9, v122, v123
	v_cvt_pk_bf16_f32 v10, v124, v125
	v_cvt_pk_bf16_f32 v11, v126, v127
	v_cvt_pk_bf16_f32 v4, v72, v73
	v_cvt_pk_bf16_f32 v5, v74, v75
	v_cvt_pk_bf16_f32 v6, v80, v81
	v_cvt_pk_bf16_f32 v7, v82, v83
	v_cvt_pk_bf16_f32 v0, v92, v93
	v_cvt_pk_bf16_f32 v1, v94, v95
	v_cvt_pk_bf16_f32 v2, v104, v105
	v_cvt_pk_bf16_f32 v3, v106, v107
	s_cbranch_scc0 .LBB0_244
	s_add_i32 s0, s56, s49
	v_or_b32_e32 v36, s0, v162
	v_readlane_b32 s0, v254, 24
	s_or_b32 s0, s78, s0
	v_mov_b64_e32 v[38:39], s[50:51]
	v_or_b32_e32 v50, s0, v161
	v_ashrrev_i32_e32 v37, 31, v36
	v_mad_i64_i32 v[40:41], s[0:1], v50, s46, v[38:39]
	v_or_b32_e32 v42, 16, v50
	v_or_b32_e32 v48, 0x80, v50
	v_or_b32_e32 v50, 0x90, v50
	v_lshlrev_b64 v[36:37], 1, v[36:37]
	v_mad_i64_i32 v[42:43], s[0:1], v42, s46, v[38:39]
	v_mad_i64_i32 v[48:49], s[0:1], v48, s46, v[38:39]
	v_mad_i64_i32 v[38:39], s[0:1], v50, s46, v[38:39]
	v_lshl_add_u64 v[40:41], v[40:41], 0, v[36:37]
	v_lshl_add_u64 v[42:43], v[42:43], 0, v[36:37]
	v_lshl_add_u64 v[48:49], v[48:49], 0, v[36:37]
	v_lshl_add_u64 v[36:37], v[38:39], 0, v[36:37]
	global_store_dwordx4 v[40:41], v[144:147], off nt
	global_store_dwordx4 v[40:41], v[140:143], off offset:16 nt
	global_store_dwordx4 v[42:43], v[136:139], off nt
	global_store_dwordx4 v[42:43], v[132:135], off offset:16 nt
	global_store_dwordx4 v[48:49], v[128:131], off nt
	global_store_dwordx4 v[48:49], v[52:55], off offset:16 nt
	global_store_dwordx4 v[36:37], v[44:47], off nt
	global_store_dwordx4 v[36:37], v[32:35], off offset:16 nt
	global_store_dwordx4 v[40:41], v[28:31], off offset:256 nt
	global_store_dwordx4 v[40:41], v[24:27], off offset:272 nt
	global_store_dwordx4 v[42:43], v[20:23], off offset:256 nt
	global_store_dwordx4 v[42:43], v[16:19], off offset:272 nt
	global_store_dwordx4 v[48:49], v[12:15], off offset:256 nt
	global_store_dwordx4 v[48:49], v[8:11], off offset:272 nt
	global_store_dwordx4 v[36:37], v[4:7], off offset:256 nt
	global_store_dwordx4 v[36:37], v[0:3], off offset:272 nt
	s_mov_b64 s[0:1], 0
.LBB0_244:
	s_andn2_b64 vcc, exec, s[0:1]
	s_cbranch_vccnz .LBB0_205
	s_add_i32 s0, s56, s49
	v_or_b32_e32 v42, s0, v162
	s_mov_b32 s4, 0xfe03f81
	v_readlane_b32 s0, v254, 25
	v_mul_hi_i32 v36, v42, s4
	s_add_i32 s0, s0, s78
	v_lshrrev_b32_e32 v37, 31, v36
	v_ashrrev_i32_e32 v36, 7, v36
	v_or_b32_e32 v43, s0, v161
	v_add_u32_e32 v37, v36, v37
	s_movk_i32 s5, 0xf7f0
	v_readlane_b32 s0, v254, 10
	v_mad_i32_i24 v36, v37, s5, v42
	v_readlane_b32 s1, v254, 11
	v_lshl_add_u32 v48, v37, 9, v43
	v_ashrrev_i32_e32 v37, 31, v36
	v_mov_b64_e32 v[38:39], s[0:1]
	v_mad_i64_i32 v[40:41], s[0:1], v48, s62, v[38:39]
	v_lshlrev_b64 v[36:37], 1, v[36:37]
	v_lshl_add_u64 v[40:41], v[40:41], 0, v[36:37]
	global_store_dwordx4 v[40:41], v[144:147], off nt
	global_store_dwordx4 v[40:41], v[140:143], off offset:16 nt
	v_or_b32_e32 v40, 16, v48
	v_mad_i64_i32 v[40:41], s[0:1], v40, s62, v[38:39]
	v_lshl_add_u64 v[40:41], v[40:41], 0, v[36:37]
	global_store_dwordx4 v[40:41], v[136:139], off nt
	global_store_dwordx4 v[40:41], v[132:135], off offset:16 nt
	v_or_b32_e32 v40, 0x80, v48
	v_mad_i64_i32 v[40:41], s[0:1], v40, s62, v[38:39]
	v_lshl_add_u64 v[40:41], v[40:41], 0, v[36:37]
	global_store_dwordx4 v[40:41], v[128:131], off nt
	global_store_dwordx4 v[40:41], v[52:55], off offset:16 nt
	v_or_b32_e32 v40, 0x90, v48
	v_mad_i64_i32 v[40:41], s[0:1], v40, s62, v[38:39]
	v_lshl_add_u64 v[36:37], v[40:41], 0, v[36:37]
	global_store_dwordx4 v[36:37], v[44:47], off nt
	global_store_dwordx4 v[36:37], v[32:35], off offset:16 nt
	s_nop 1
	v_add_u32_e32 v32, 0x80, v42
	v_mul_hi_i32 v33, v32, s4
	v_lshrrev_b32_e32 v34, 31, v33
	v_ashrrev_i32_e32 v33, 7, v33
	v_add_u32_e32 v33, v33, v34
	v_mad_i32_i24 v32, v33, s5, v32
	v_lshl_add_u32 v36, v33, 9, v43
	v_ashrrev_i32_e32 v33, 31, v32
	v_mad_i64_i32 v[34:35], s[0:1], v36, s62, v[38:39]
	v_lshlrev_b64 v[32:33], 1, v[32:33]
	v_lshl_add_u64 v[34:35], v[34:35], 0, v[32:33]
	global_store_dwordx4 v[34:35], v[28:31], off nt
	global_store_dwordx4 v[34:35], v[24:27], off offset:16 nt
	s_nop 1
	v_or_b32_e32 v24, 16, v36
	v_mad_i64_i32 v[24:25], s[0:1], v24, s62, v[38:39]
	v_lshl_add_u64 v[24:25], v[24:25], 0, v[32:33]
	global_store_dwordx4 v[24:25], v[20:23], off nt
	global_store_dwordx4 v[24:25], v[16:19], off offset:16 nt
	s_nop 1
	v_or_b32_e32 v16, 0x80, v36
	v_mad_i64_i32 v[16:17], s[0:1], v16, s62, v[38:39]
	v_lshl_add_u64 v[16:17], v[16:17], 0, v[32:33]
	global_store_dwordx4 v[16:17], v[12:15], off nt
	global_store_dwordx4 v[16:17], v[8:11], off offset:16 nt
	s_nop 1
	v_or_b32_e32 v8, 0x90, v36
	v_mad_i64_i32 v[8:9], s[0:1], v8, s62, v[38:39]
	v_lshl_add_u64 v[8:9], v[8:9], 0, v[32:33]
	global_store_dwordx4 v[8:9], v[4:7], off nt
	global_store_dwordx4 v[8:9], v[0:3], off offset:16 nt
	s_branch .LBB0_205
